# ssd_out: 40 of 64 decay-mask elements made branch-free with vector LDS reads
# speedup vs baseline: 1.2244x; 1.0046x over previous
.LBB0_453:
	v_lshl_add_u32 v104, v169, 2, s91
	ds_read2st64_b32 v[160:161], v104 offset1:2
	ds_read_b128 v[104:107], v193
	ds_read_b128 v[108:111], v194
	ds_read_b128 v[112:115], v193 offset:64
	v_readlane_b32 s0, v254, 15
	v_mov_b32_e32 v209, 0
	s_waitcnt lgkmcnt(2)
	v_mfma_f32_16x16x32_bf16 v[104:107], v[104:107], v[68:71], 0
	v_lshl_add_u32 v204, v150, 2, s91
	v_mov_b32_e32 v210, 0
	v_readlane_b32 s1, v254, 16
	s_waitcnt lgkmcnt(0)
	v_mfma_f32_16x16x32_bf16 v[104:107], v[112:115], v[64:67], v[104:107]
	ds_read_b128 v[112:115], v194 offset:64
	ds_read_b128 v[128:131], v198 offset:64
	ds_read_b128 v[120:123], v196 offset:64
	v_mfma_f32_16x16x32_bf16 v[108:111], v[108:111], v[68:71], 0
	ds_read_b128 v[124:127], v199
	ds_read_b128 v[116:119], v197
	ds_read_b128 v[136:139], v200 offset:64
	s_waitcnt lgkmcnt(5)
	v_mfma_f32_16x16x32_bf16 v[108:111], v[112:115], v[64:67], v[108:111]
	ds_read_b128 v[112:115], v193 offset:128
	ds_read_b128 v[132:135], v201
	s_waitcnt lgkmcnt(1)
	v_mfma_f32_16x16x32_bf16 v[104:107], v[112:115], v[60:63], v[104:107]
	ds_read_b128 v[112:115], v194 offset:128
	s_waitcnt lgkmcnt(0)
	v_mfma_f32_16x16x32_bf16 v[108:111], v[112:115], v[60:63], v[108:111]
	ds_read_b128 v[112:115], v193 offset:192
	s_waitcnt lgkmcnt(0)
	v_mfma_f32_16x16x32_bf16 v[104:107], v[112:115], v[56:59], v[104:107]
	ds_read_b128 v[112:115], v194 offset:192
	s_waitcnt lgkmcnt(0)
	v_mfma_f32_16x16x32_bf16 v[108:111], v[112:115], v[56:59], v[108:111]
	ds_read_b128 v[112:115], v196
	s_waitcnt lgkmcnt(0)
	v_mfma_f32_16x16x32_bf16 v[112:115], v[112:115], v[68:71], 0
	v_mfma_f32_16x16x32_bf16 v[112:115], v[120:123], v[64:67], v[112:115]
	ds_read_b128 v[120:123], v197 offset:64
	v_mfma_f32_16x16x32_bf16 v[116:119], v[116:119], v[68:71], 0
	s_waitcnt lgkmcnt(0)
	v_mfma_f32_16x16x32_bf16 v[116:119], v[120:123], v[64:67], v[116:119]
	ds_read_b128 v[120:123], v196 offset:128
	s_waitcnt lgkmcnt(0)
	v_mfma_f32_16x16x32_bf16 v[112:115], v[120:123], v[60:63], v[112:115]
	ds_read_b128 v[120:123], v197 offset:128
	s_waitcnt lgkmcnt(0)
	v_mfma_f32_16x16x32_bf16 v[120:123], v[120:123], v[60:63], v[116:119]
	s_nop 2
	ds_read_b128 v[116:119], v196 offset:192
	s_waitcnt lgkmcnt(0)
	v_mfma_f32_16x16x32_bf16 v[116:119], v[116:119], v[56:59], v[112:115]
	s_nop 2
	ds_read_b128 v[112:115], v197 offset:192
	s_waitcnt lgkmcnt(0)
	v_mfma_f32_16x16x32_bf16 v[120:123], v[112:115], v[56:59], v[120:123]
	ds_read_b128 v[112:115], v198
	s_waitcnt lgkmcnt(0)
	v_mfma_f32_16x16x32_bf16 v[112:115], v[112:115], v[68:71], 0
	v_mfma_f32_16x16x32_bf16 v[112:115], v[128:131], v[64:67], v[112:115]
	ds_read_b128 v[128:131], v199 offset:64
	v_mfma_f32_16x16x32_bf16 v[124:127], v[124:127], v[68:71], 0
	s_waitcnt lgkmcnt(0)
	v_mfma_f32_16x16x32_bf16 v[124:127], v[128:131], v[64:67], v[124:127]
	ds_read_b128 v[128:131], v198 offset:128
	s_waitcnt lgkmcnt(0)
	v_mfma_f32_16x16x32_bf16 v[112:115], v[128:131], v[60:63], v[112:115]
	ds_read_b128 v[128:131], v199 offset:128
	s_waitcnt lgkmcnt(0)
	v_mfma_f32_16x16x32_bf16 v[128:131], v[128:131], v[60:63], v[124:127]
	s_nop 2
	ds_read_b128 v[124:127], v198 offset:192
	s_waitcnt lgkmcnt(0)
	v_mfma_f32_16x16x32_bf16 v[124:127], v[124:127], v[56:59], v[112:115]
	s_nop 2
	ds_read_b128 v[112:115], v199 offset:192
	s_waitcnt lgkmcnt(0)
	v_mfma_f32_16x16x32_bf16 v[128:131], v[112:115], v[56:59], v[128:131]
	ds_read_b128 v[112:115], v200
	s_waitcnt lgkmcnt(0)
	v_mfma_f32_16x16x32_bf16 v[112:115], v[112:115], v[68:71], 0
	v_mfma_f32_16x16x32_bf16 v[112:115], v[136:139], v[64:67], v[112:115]
	ds_read_b128 v[136:139], v201 offset:64
	v_mfma_f32_16x16x32_bf16 v[132:135], v[132:135], v[68:71], 0
	s_waitcnt lgkmcnt(0)
	v_mfma_f32_16x16x32_bf16 v[132:135], v[136:139], v[64:67], v[132:135]
	ds_read_b128 v[136:139], v200 offset:128
	s_waitcnt lgkmcnt(0)
	v_mfma_f32_16x16x32_bf16 v[112:115], v[136:139], v[60:63], v[112:115]
	ds_read_b128 v[136:139], v201 offset:128
	s_waitcnt lgkmcnt(0)
	v_mfma_f32_16x16x32_bf16 v[136:139], v[136:139], v[60:63], v[132:135]
	s_nop 2
	ds_read_b128 v[132:135], v200 offset:192
	s_waitcnt lgkmcnt(0)
	v_mfma_f32_16x16x32_bf16 v[132:135], v[132:135], v[56:59], v[112:115]
	s_nop 2
	ds_read_b128 v[112:115], v201 offset:192
	s_waitcnt lgkmcnt(0)
	v_mfma_f32_16x16x32_bf16 v[136:139], v[112:115], v[56:59], v[136:139]
	s_mov_b32 s91, s6
	ds_read_b128 v[248:251], v204 offset:0
	ds_read_b64 v[238:239], v204 offset:512
	ds_read_b32 v247, v204 offset:520
	ds_read_b32 v252, v204 offset:524
	s_waitcnt lgkmcnt(0)
	v_readlane_b32 s0, v254, 15
	v_readlane_b32 s1, v254, 16
	v_readlane_b32 s82, v254, 19
	v_readlane_b32 s83, v254, 20
	v_sub_f32_e32 v248, v160, v248
	v_sub_f32_e32 v238, v161, v238
	v_mul_f32_e32 v248, 0x3fb8aa3b, v248
	v_mul_f32_e32 v238, 0x3fb8aa3b, v238
	v_exp_f32_e32 v248, v248
	v_exp_f32_e32 v238, v238
	v_mul_f32_e32 v248, v72, v248
	v_mul_f32_e32 v238, v72, v238
	v_cndmask_b32_e64 v210, 0, v248, s[0:1]
	v_cndmask_b32_e64 v205, 0, v238, s[82:83]
	v_readlane_b32 s0, v254, 17
	v_readlane_b32 s1, v254, 18
	v_readlane_b32 s82, v254, 21
	v_readlane_b32 s83, v254, 22
	v_sub_f32_e32 v249, v160, v249
	v_sub_f32_e32 v239, v161, v239
	v_mul_f32_e32 v249, 0x3fb8aa3b, v249
	v_mul_f32_e32 v239, 0x3fb8aa3b, v239
	v_exp_f32_e32 v249, v249
	v_exp_f32_e32 v239, v239
	v_mul_f32_e32 v249, v73, v249
	v_mul_f32_e32 v239, v73, v239
	v_cndmask_b32_e64 v209, 0, v249, s[0:1]
	v_cndmask_b32_e64 v206, 0, v239, s[82:83]
	v_readlane_b32 s0, v254, 23
	v_readlane_b32 s1, v254, 24
	v_readlane_b32 s82, v254, 25
	v_readlane_b32 s83, v254, 26
	v_sub_f32_e32 v250, v160, v250
	v_sub_f32_e32 v247, v161, v247
	v_mul_f32_e32 v250, 0x3fb8aa3b, v250
	v_mul_f32_e32 v247, 0x3fb8aa3b, v247
	v_exp_f32_e32 v250, v250
	v_exp_f32_e32 v247, v247
	v_mul_f32_e32 v250, v74, v250
	v_mul_f32_e32 v247, v74, v247
	v_cndmask_b32_e64 v212, 0, v250, s[0:1]
	v_cndmask_b32_e64 v207, 0, v247, s[82:83]
	v_readlane_b32 s0, v254, 27
	v_readlane_b32 s1, v254, 28
	v_readlane_b32 s82, v254, 29
	v_readlane_b32 s83, v254, 30
	v_sub_f32_e32 v251, v160, v251
	v_sub_f32_e32 v252, v161, v252
	v_mul_f32_e32 v251, 0x3fb8aa3b, v251
	v_mul_f32_e32 v252, 0x3fb8aa3b, v252
	v_exp_f32_e32 v251, v251
	v_exp_f32_e32 v252, v252
	v_mul_f32_e32 v251, v75, v251
	v_mul_f32_e32 v252, v75, v252
	v_cndmask_b32_e64 v214, 0, v251, s[0:1]
	v_cndmask_b32_e64 v208, 0, v252, s[82:83]
	v_mov_b32_e32 v216, 0
.LBB0_455:
.LBB0_457:
.LBB0_459:
.LBB0_461:
.LBB0_463:
.LBB0_465:
.LBB0_467:
.LBB0_469:
	ds_read_b128 v[248:251], v204 offset:64
	ds_read_b64 v[238:239], v204 offset:576
	ds_read_b32 v247, v204 offset:584
	ds_read_b32 v252, v204 offset:588
	s_waitcnt lgkmcnt(0)
	v_readlane_b32 s0, v254, 31
	v_readlane_b32 s1, v254, 32
	v_readlane_b32 s82, v254, 33
	v_readlane_b32 s83, v254, 34
	v_sub_f32_e32 v248, v160, v248
	v_sub_f32_e32 v238, v161, v238
	v_mul_f32_e32 v248, 0x3fb8aa3b, v248
	v_mul_f32_e32 v238, 0x3fb8aa3b, v238
	v_exp_f32_e32 v248, v248
	v_exp_f32_e32 v238, v238
	v_mul_f32_e32 v248, v76, v248
	v_mul_f32_e32 v238, v76, v238
	v_cndmask_b32_e64 v216, 0, v248, s[0:1]
	v_cndmask_b32_e64 v211, 0, v238, s[82:83]
	v_readlane_b32 s0, v254, 35
	v_readlane_b32 s1, v254, 36
	v_readlane_b32 s82, v254, 37
	v_readlane_b32 s83, v254, 38
	v_sub_f32_e32 v249, v160, v249
	v_sub_f32_e32 v239, v161, v239
	v_mul_f32_e32 v249, 0x3fb8aa3b, v249
	v_mul_f32_e32 v239, 0x3fb8aa3b, v239
	v_exp_f32_e32 v249, v249
	v_exp_f32_e32 v239, v239
	v_mul_f32_e32 v249, v77, v249
	v_mul_f32_e32 v239, v77, v239
	v_cndmask_b32_e64 v218, 0, v249, s[0:1]
	v_cndmask_b32_e64 v213, 0, v239, s[82:83]
	v_readlane_b32 s0, v254, 39
	v_readlane_b32 s1, v254, 40
	v_readlane_b32 s82, v254, 41
	v_readlane_b32 s83, v254, 42
	v_sub_f32_e32 v250, v160, v250
	v_sub_f32_e32 v247, v161, v247
	v_mul_f32_e32 v250, 0x3fb8aa3b, v250
	v_mul_f32_e32 v247, 0x3fb8aa3b, v247
	v_exp_f32_e32 v250, v250
	v_exp_f32_e32 v247, v247
	v_mul_f32_e32 v250, v78, v250
	v_mul_f32_e32 v247, v78, v247
	v_cndmask_b32_e64 v219, 0, v250, s[0:1]
	v_cndmask_b32_e64 v215, 0, v247, s[82:83]
	v_readlane_b32 s0, v254, 43
	v_readlane_b32 s1, v254, 44
	v_readlane_b32 s82, v254, 45
	v_readlane_b32 s83, v254, 46
	v_sub_f32_e32 v251, v160, v251
	v_sub_f32_e32 v252, v161, v252
	v_mul_f32_e32 v251, 0x3fb8aa3b, v251
	v_mul_f32_e32 v252, 0x3fb8aa3b, v252
	v_exp_f32_e32 v251, v251
	v_exp_f32_e32 v252, v252
	v_mul_f32_e32 v251, v79, v251
	v_mul_f32_e32 v252, v79, v252
	v_cndmask_b32_e64 v220, 0, v251, s[0:1]
	v_cndmask_b32_e64 v217, 0, v252, s[82:83]
.LBB0_471:
.LBB0_473:
.LBB0_475:
.LBB0_477:
.LBB0_479:
.LBB0_481:
.LBB0_483:
.LBB0_485:
	v_mul_f32_e32 v112, 0x3fb8aa3b, v160
	v_exp_f32_e32 v234, v112
	v_mul_f32_e32 v112, 0x3fb8aa3b, v161
	v_exp_f32_e32 v236, v112
	v_readlane_b32 s0, v254, 47
	v_pk_mul_f32 v[228:229], v[234:235], v[118:119] op_sel_hi:[0,1]
	v_pk_mul_f32 v[226:227], v[234:235], v[116:117] op_sel_hi:[0,1]
	v_pk_mul_f32 v[118:119], v[236:237], v[122:123] op_sel_hi:[0,1]
	v_pk_mul_f32 v[116:117], v[236:237], v[120:121] op_sel_hi:[0,1]
	v_pk_mul_f32 v[232:233], v[234:235], v[126:127] op_sel_hi:[0,1]
	v_pk_mul_f32 v[230:231], v[234:235], v[124:125] op_sel_hi:[0,1]
	ds_read_b64_tr_b16 v[122:123], v195 offset:6400
	ds_read_b64_tr_b16 v[120:121], v195 offset:4096
	ds_read_b64_tr_b16 v[124:125], v195 offset:4128
	ds_read_b64_tr_b16 v[126:127], v195 offset:6432
	v_pk_mul_f32 v[224:225], v[234:235], v[106:107] op_sel_hi:[0,1]
	v_pk_mul_f32 v[114:115], v[236:237], v[110:111] op_sel_hi:[0,1]
	v_pk_mul_f32 v[112:113], v[236:237], v[108:109] op_sel_hi:[0,1]
	v_pk_mul_f32 v[110:111], v[236:237], v[130:131] op_sel_hi:[0,1]
	v_pk_mul_f32 v[108:109], v[236:237], v[128:129] op_sel_hi:[0,1]
	v_pk_mul_f32 v[106:107], v[236:237], v[138:139] op_sel_hi:[0,1]
	v_cvt_pk_bf16_f32 v138, v216, v218
	v_cvt_pk_bf16_f32 v139, v219, v220
	ds_read_b64_tr_b16 v[128:129], v195 offset:4160
	ds_read_b64_tr_b16 v[130:131], v195 offset:6464
	ds_read_b64_tr_b16 v[218:219], v195 offset:4192
	ds_read_b64_tr_b16 v[220:221], v195 offset:6496
	v_pk_mul_f32 v[222:223], v[234:235], v[104:105] op_sel_hi:[0,1]
	v_pk_mul_f32 v[134:135], v[234:235], v[134:135] op_sel_hi:[0,1]
	v_pk_mul_f32 v[132:133], v[234:235], v[132:133] op_sel_hi:[0,1]
	v_pk_mul_f32 v[104:105], v[236:237], v[136:137] op_sel_hi:[0,1]
	v_cvt_pk_bf16_f32 v136, v210, v209
	v_cvt_pk_bf16_f32 v137, v212, v214
	v_readlane_b32 s1, v254, 48
	s_andn2_b64 vcc, exec, s[0:1]
	s_waitcnt lgkmcnt(6)
	v_mfma_f32_16x16x32_bf16 v[120:123], v[120:123], v[136:139], v[222:225]
	s_waitcnt lgkmcnt(4)
	v_mfma_f32_16x16x32_bf16 v[124:127], v[124:127], v[136:139], v[226:229]
	s_waitcnt lgkmcnt(2)
	v_mfma_f32_16x16x32_bf16 v[128:131], v[128:131], v[136:139], v[230:233]
	s_waitcnt lgkmcnt(0)
	v_mfma_f32_16x16x32_bf16 v[132:135], v[218:221], v[136:139], v[132:135]
	s_cbranch_vccnz .LBB0_487
	v_cvt_pk_bf16_f32 v136, v205, v206
	v_cvt_pk_bf16_f32 v137, v207, v208
	v_cvt_pk_bf16_f32 v138, v211, v213
	ds_read_b64_tr_b16 v[208:209], v195 offset:24832
	ds_read_b64_tr_b16 v[206:207], v195 offset:22528
	ds_read_b64_tr_b16 v[210:211], v195 offset:22560
	v_cvt_pk_bf16_f32 v139, v215, v217
	ds_read_b64_tr_b16 v[212:213], v195 offset:24864
	s_waitcnt lgkmcnt(2)
	v_mfma_f32_16x16x32_bf16 v[112:115], v[206:209], v[136:139], v[112:115]
	ds_read_b64_tr_b16 v[206:207], v195 offset:22592
	ds_read_b64_tr_b16 v[208:209], v195 offset:24896
	s_waitcnt lgkmcnt(0)
	v_mfma_f32_16x16x32_bf16 v[108:111], v[206:209], v[136:139], v[108:111]
	ds_read_b64_tr_b16 v[206:207], v195 offset:22624
	ds_read_b64_tr_b16 v[208:209], v195 offset:24928
	v_mfma_f32_16x16x32_bf16 v[116:119], v[210:213], v[136:139], v[116:119]
	s_waitcnt lgkmcnt(0)
	v_mfma_f32_16x16x32_bf16 v[104:107], v[206:209], v[136:139], v[104:107]
.LBB0_487:
	ds_read_b128 v[248:251], v204 offset:128
	ds_read_b64 v[238:239], v204 offset:640
	ds_read_b32 v247, v204 offset:648
	ds_read_b32 v252, v204 offset:652
	s_waitcnt lgkmcnt(0)
	v_readlane_b32 s0, v254, 51
	v_readlane_b32 s1, v254, 52
	v_readlane_b32 s82, v254, 53
	v_readlane_b32 s83, v254, 54
	v_sub_f32_e32 v248, v160, v248
	v_sub_f32_e32 v238, v161, v238
	v_mul_f32_e32 v248, 0x3fb8aa3b, v248
	v_mul_f32_e32 v238, 0x3fb8aa3b, v238
	v_exp_f32_e32 v248, v248
	v_exp_f32_e32 v238, v238
	v_mul_f32_e32 v248, v80, v248
	v_mul_f32_e32 v238, v80, v238
	v_cndmask_b32_e64 v206, 0, v248, s[0:1]
	v_cndmask_b32_e64 v136, 0, v238, s[82:83]
	v_readlane_b32 s0, v254, 55
	v_readlane_b32 s1, v254, 56
	v_readlane_b32 s82, v254, 57
	v_readlane_b32 s83, v254, 58
	v_sub_f32_e32 v249, v160, v249
	v_sub_f32_e32 v239, v161, v239
	v_mul_f32_e32 v249, 0x3fb8aa3b, v249
	v_mul_f32_e32 v239, 0x3fb8aa3b, v239
	v_exp_f32_e32 v249, v249
	v_exp_f32_e32 v239, v239
	v_mul_f32_e32 v249, v81, v249
	v_mul_f32_e32 v239, v81, v239
	v_cndmask_b32_e64 v208, 0, v249, s[0:1]
	v_cndmask_b32_e64 v137, 0, v239, s[82:83]
	v_readlane_b32 s0, v254, 59
	v_readlane_b32 s1, v254, 60
	v_readlane_b32 s82, v254, 61
	v_readlane_b32 s83, v254, 62
	v_sub_f32_e32 v250, v160, v250
	v_sub_f32_e32 v247, v161, v247
	v_mul_f32_e32 v250, 0x3fb8aa3b, v250
	v_mul_f32_e32 v247, 0x3fb8aa3b, v247
	v_exp_f32_e32 v250, v250
	v_exp_f32_e32 v247, v247
	v_mul_f32_e32 v250, v82, v250
	v_mul_f32_e32 v247, v82, v247
	v_cndmask_b32_e64 v210, 0, v250, s[0:1]
	v_cndmask_b32_e64 v138, 0, v247, s[82:83]
	v_readlane_b32 s0, v254, 63
	v_readlane_b32 s1, v255, 0
	v_readlane_b32 s82, v255, 1
	v_readlane_b32 s83, v255, 2
	v_sub_f32_e32 v251, v160, v251
	v_sub_f32_e32 v252, v161, v252
	v_mul_f32_e32 v251, 0x3fb8aa3b, v251
	v_mul_f32_e32 v252, 0x3fb8aa3b, v252
	v_exp_f32_e32 v251, v251
	v_exp_f32_e32 v252, v252
	v_mul_f32_e32 v251, v83, v251
	v_mul_f32_e32 v252, v83, v252
	v_cndmask_b32_e64 v212, 0, v251, s[0:1]
	v_cndmask_b32_e64 v139, 0, v252, s[82:83]
.LBB0_489:
.LBB0_491:
.LBB0_493:
.LBB0_495:
.LBB0_497:
.LBB0_499:
.LBB0_501:
.LBB0_503:
	ds_read_b128 v[248:251], v204 offset:192
	ds_read_b64 v[238:239], v204 offset:704
	ds_read_b32 v247, v204 offset:712
	ds_read_b32 v252, v204 offset:716
	s_waitcnt lgkmcnt(0)
	v_readlane_b32 s0, v255, 3
	v_readlane_b32 s1, v255, 4
	v_readlane_b32 s82, v255, 5
	v_readlane_b32 s83, v255, 6
	v_sub_f32_e32 v248, v160, v248
	v_sub_f32_e32 v238, v161, v238
	v_mul_f32_e32 v248, 0x3fb8aa3b, v248
	v_mul_f32_e32 v238, 0x3fb8aa3b, v238
	v_exp_f32_e32 v248, v248
	v_exp_f32_e32 v238, v238
	v_mul_f32_e32 v248, v84, v248
	v_mul_f32_e32 v238, v84, v238
	v_cndmask_b32_e64 v213, 0, v248, s[0:1]
	v_cndmask_b32_e64 v205, 0, v238, s[82:83]
	v_readlane_b32 s0, v255, 7
	v_readlane_b32 s1, v255, 8
	v_readlane_b32 s82, v255, 9
	v_readlane_b32 s83, v255, 10
	v_sub_f32_e32 v249, v160, v249
	v_sub_f32_e32 v239, v161, v239
	v_mul_f32_e32 v249, 0x3fb8aa3b, v249
	v_mul_f32_e32 v239, 0x3fb8aa3b, v239
	v_exp_f32_e32 v249, v249
	v_exp_f32_e32 v239, v239
	v_mul_f32_e32 v249, v85, v249
	v_mul_f32_e32 v239, v85, v239
	v_cndmask_b32_e64 v214, 0, v249, s[0:1]
	v_cndmask_b32_e64 v207, 0, v239, s[82:83]
	v_readlane_b32 s0, v255, 11
	v_readlane_b32 s1, v255, 12
	v_readlane_b32 s82, v255, 13
	v_readlane_b32 s83, v255, 14
	v_sub_f32_e32 v250, v160, v250
	v_sub_f32_e32 v247, v161, v247
	v_mul_f32_e32 v250, 0x3fb8aa3b, v250
	v_mul_f32_e32 v247, 0x3fb8aa3b, v247
	v_exp_f32_e32 v250, v250
	v_exp_f32_e32 v247, v247
	v_mul_f32_e32 v250, v86, v250
	v_mul_f32_e32 v247, v86, v247
	v_cndmask_b32_e64 v215, 0, v250, s[0:1]
	v_cndmask_b32_e64 v209, 0, v247, s[82:83]
	v_readlane_b32 s0, v255, 15
	v_readlane_b32 s1, v255, 16
	v_readlane_b32 s82, v255, 17
	v_readlane_b32 s83, v255, 18
	v_sub_f32_e32 v251, v160, v251
	v_sub_f32_e32 v252, v161, v252
	v_mul_f32_e32 v251, 0x3fb8aa3b, v251
	v_mul_f32_e32 v252, 0x3fb8aa3b, v252
	v_exp_f32_e32 v251, v251
	v_exp_f32_e32 v252, v252
	v_mul_f32_e32 v251, v87, v251
	v_mul_f32_e32 v252, v87, v252
	v_cndmask_b32_e64 v216, 0, v251, s[0:1]
	v_cndmask_b32_e64 v211, 0, v252, s[82:83]
.LBB0_505:
.LBB0_507:
.LBB0_509:
.LBB0_511:
.LBB0_513:
.LBB0_515:
.LBB0_517:
.LBB0_519:
	v_readlane_b32 s0, v254, 49
	v_readlane_b32 s1, v254, 50
	s_andn2_b64 vcc, exec, s[0:1]
	s_cbranch_vccnz .LBB0_521
	v_cvt_pk_bf16_f32 v219, v210, v212
	v_cvt_pk_bf16_f32 v220, v213, v214
	v_cvt_pk_bf16_f32 v221, v215, v216
	ds_read_b64_tr_b16 v[214:215], v195 offset:11008
	ds_read_b64_tr_b16 v[212:213], v195 offset:8704
	ds_read_b64_tr_b16 v[222:223], v195 offset:8736
	v_cvt_pk_bf16_f32 v218, v206, v208
	ds_read_b64_tr_b16 v[224:225], v195 offset:11040
	s_waitcnt lgkmcnt(2)
	v_mfma_f32_16x16x32_bf16 v[120:123], v[212:215], v[218:221], v[120:123]
	ds_read_b64_tr_b16 v[212:213], v195 offset:8768
	ds_read_b64_tr_b16 v[214:215], v195 offset:11072
	s_waitcnt lgkmcnt(0)
	v_mfma_f32_16x16x32_bf16 v[128:131], v[212:215], v[218:221], v[128:131]
	ds_read_b64_tr_b16 v[212:213], v195 offset:8800
	ds_read_b64_tr_b16 v[214:215], v195 offset:11104
	v_mfma_f32_16x16x32_bf16 v[124:127], v[222:225], v[218:221], v[124:127]
	s_waitcnt lgkmcnt(0)
	v_mfma_f32_16x16x32_bf16 v[132:135], v[212:215], v[218:221], v[132:135]

.LBB0_523:
	ds_read_b128 v[248:251], v204 offset:256
	ds_read_b64 v[238:239], v204 offset:768
	ds_read_b32 v247, v204 offset:776
	ds_read_b32 v252, v204 offset:780
	s_waitcnt lgkmcnt(0)
	v_readlane_b32 s0, v255, 21
	v_readlane_b32 s1, v255, 22
	v_readlane_b32 s82, v255, 23
	v_readlane_b32 s83, v255, 24
	v_sub_f32_e32 v248, v160, v248
	v_sub_f32_e32 v238, v161, v238
	v_mul_f32_e32 v248, 0x3fb8aa3b, v248
	v_mul_f32_e32 v238, 0x3fb8aa3b, v238
	v_exp_f32_e32 v248, v248
	v_exp_f32_e32 v238, v238
	v_mul_f32_e32 v248, v88, v248
	v_mul_f32_e32 v238, v88, v238
	v_cndmask_b32_e64 v139, 0, v248, s[0:1]
	v_cndmask_b32_e64 v136, 0, v238, s[82:83]
	v_readlane_b32 s0, v255, 25
	v_readlane_b32 s1, v255, 26
	v_readlane_b32 s82, v255, 27
	v_readlane_b32 s83, v255, 28
	v_sub_f32_e32 v249, v160, v249
	v_sub_f32_e32 v239, v161, v239
	v_mul_f32_e32 v249, 0x3fb8aa3b, v249
	v_mul_f32_e32 v239, 0x3fb8aa3b, v239
	v_exp_f32_e32 v249, v249
	v_exp_f32_e32 v239, v239
	v_mul_f32_e32 v249, v89, v249
	v_mul_f32_e32 v239, v89, v239
	v_cndmask_b32_e64 v207, 0, v249, s[0:1]
	v_cndmask_b32_e64 v137, 0, v239, s[82:83]
	v_readlane_b32 s0, v255, 29
	v_readlane_b32 s1, v255, 30
	v_readlane_b32 s82, v255, 31
	v_readlane_b32 s83, v255, 32
	v_sub_f32_e32 v250, v160, v250
	v_sub_f32_e32 v247, v161, v247
	v_mul_f32_e32 v250, 0x3fb8aa3b, v250
	v_mul_f32_e32 v247, 0x3fb8aa3b, v247
	v_exp_f32_e32 v250, v250
	v_exp_f32_e32 v247, v247
	v_mul_f32_e32 v250, v90, v250
	v_mul_f32_e32 v247, v90, v247
	v_cndmask_b32_e64 v208, 0, v250, s[0:1]
	v_cndmask_b32_e64 v138, 0, v247, s[82:83]
	v_readlane_b32 s0, v255, 33
	v_readlane_b32 s1, v255, 34
	v_readlane_b32 s82, v255, 35
	v_readlane_b32 s83, v255, 36
	v_sub_f32_e32 v251, v160, v251
	v_sub_f32_e32 v252, v161, v252
	v_mul_f32_e32 v251, 0x3fb8aa3b, v251
	v_mul_f32_e32 v252, 0x3fb8aa3b, v252
	v_exp_f32_e32 v251, v251
	v_exp_f32_e32 v252, v252
	v_mul_f32_e32 v251, v91, v251
	v_mul_f32_e32 v252, v91, v252
	v_cndmask_b32_e64 v211, 0, v251, s[0:1]
	v_cndmask_b32_e64 v205, 0, v252, s[82:83]
.LBB0_525:
.LBB0_527:
.LBB0_529:
.LBB0_531:
.LBB0_533:
.LBB0_535:
.LBB0_537:
.LBB0_539:
	v_readlane_b32 s0, v255, 37
	v_mov_b32_e32 v206, 0
	v_mov_b32_e32 v212, 0
	v_readlane_b32 s1, v255, 38
	s_and_saveexec_b64 s[82:83], s[0:1]
	s_cbranch_execz .LBB0_541
	ds_read_b32 v209, v204 offset:320
	s_waitcnt lgkmcnt(0)
	v_sub_f32_e32 v209, v160, v209
	v_mul_f32_e32 v209, 0x3fb8aa3b, v209
	v_exp_f32_e32 v209, v209
	s_nop 0
	v_mul_f32_e32 v212, v92, v209
